# attention loop back edge rotated (docs 7.11): one conditional branch back to the head, loop-carried copy moved before the test
# speedup vs baseline: 1.0018x; 1.0018x over previous
.LBB0_441:
	v_fma_f32 v64, v174, v159, v176
	s_add_i32 s68, s68, 2
	v_fma_f32 v159, v64, v179, v180
	v_mov_b32_e32 v174, v177
	s_cmp_gt_u32 s68, 32
	s_cbranch_scc0 .LBB0_433
